# GEMM epilogues: packed v_pk_mul_f32 / v_pk_add_f32 replaced by scalar f32 pairs (bit-identical)
# speedup vs baseline: 1.0089x; 1.0021x over previous
; __device__ __forceinline__ unsigned cvt_pk_bf16(float lo, float hi) { unsigned r; asm volatile("v_cvt_pk_bf16_f32 %0, %1, %2" : "=v"(r) : "v"(lo), "v"(hi)); return r; }
;     __device__ __forceinline__ void operator()(const f32x4 (&acc)[2][2][4][2], const Unit& u, int wr, int wc, int fr, int fq) const {
;         const int row0 = u.pm * BM + wr * 64 + fr; const int colt = u.pn * BM;
;         bf16_t* base; int ldc, c0; float sc = 1.f;
;         if (colt < 1024)      { base = QA;   ldc = 1024; c0 = colt;        sc = c2; }
;         else if (colt < 1536) { base = KVA;  ldc = 512;  c0 = colt - 1024; }
;         else if (colt < 2560) { base = G;    ldc = 2048; c0 = colt - 1536; }
;         else if (colt < 5632) { base = QKVB; ldc = 3072; c0 = colt - 2560; if (colt < 3584) sc = c2; }
;         else                  { base = G;    ldc = 2048; c0 = colt - 5632 + 1024; }
;         const int col0 = c0 + wc * 32 + 8 * fq;
; #pragma unroll
;         for (int ai = 0; ai < 2; ++ai)
; #pragma unroll
;             for (int m = 0; m < 4; ++m) { bf16_t* rowp = base + (size_t)(row0 + ai * HALF + m * 16) * ldc + col0;
; #pragma unroll
;                 for (int bj = 0; bj < 2; ++bj) { f32x4 v0 = acc[ai][bj][m][0] * sc, v1 = acc[ai][bj][m][1] * sc;
;                     u32x4 w; w.x = cvt_pk_bf16(v0[0], v0[1]); w.y = cvt_pk_bf16(v0[2], v0[3]); w.z = cvt_pk_bf16(v1[0], v1[1]); w.w = cvt_pk_bf16(v1[2], v1[3]);
;                     *(u32x4*)(rowp + bj * HALF) = w; } }
.LBB0_65:
	v_lshl_add_u32 v158, s46, 8, v145
	v_add_u32_e32 v146, s18, v149
	v_ashrrev_i32_e32 v154, 31, v158
	v_ashrrev_i32_e32 v147, 31, v146
	v_mul_lo_u32 v159, s48, v154
	v_mul_lo_u32 v156, s49, v158
	v_mad_u64_u32 v[154:155], s[18:19], s48, v158, 0
	v_lshl_add_u64 v[146:147], v[146:147], 1, s[50:51]
	v_add3_u32 v155, v155, v159, v156
	v_lshl_add_u64 v[154:155], v[154:155], 1, v[146:147]
	v_mul_f32_e32 v126, v126, v144
	v_mul_f32_e32 v127, v127, v144
	v_mul_f32_e32 v124, v124, v144
	v_mul_f32_e32 v125, v125, v144
	v_mul_f32_e32 v156, v122, v144
	v_mul_f32_e32 v157, v123, v144
	v_mul_f32_e32 v122, v120, v144
	v_mul_f32_e32 v123, v121, v144
	v_cvt_pk_bf16_f32 v120, v124, v125
	v_cvt_pk_bf16_f32 v121, v126, v127
	v_mul_f32_e32 v116, v116, v144
	v_mul_f32_e32 v117, v117, v144
	v_cvt_pk_bf16_f32 v122, v122, v123
	v_cvt_pk_bf16_f32 v123, v156, v157
	global_store_dwordx4 v[154:155], v[120:123], off
	v_mul_f32_e32 v118, v118, v144
	v_mul_f32_e32 v119, v119, v144
	v_mul_f32_e32 v112, v112, v144
	v_mul_f32_e32 v113, v113, v144
	v_mul_f32_e32 v120, v110, v144
	v_mul_f32_e32 v121, v111, v144
	v_mul_f32_e32 v110, v108, v144
	v_mul_f32_e32 v111, v109, v144
	v_cvt_pk_bf16_f32 v108, v116, v117
	v_cvt_pk_bf16_f32 v109, v118, v119
	v_mul_f32_e32 v100, v100, v144
	v_mul_f32_e32 v101, v101, v144
	v_cvt_pk_bf16_f32 v110, v110, v111
	v_cvt_pk_bf16_f32 v111, v120, v121
	global_store_dwordx4 v[154:155], v[108:111], off offset:256
	v_mul_f32_e32 v102, v102, v144
	v_mul_f32_e32 v103, v103, v144
	v_mul_f32_e32 v96, v96, v144
	v_mul_f32_e32 v97, v97, v144
	v_or_b32_e32 v108, 16, v158
	v_mul_lo_u32 v110, s49, v108
	v_mad_u64_u32 v[108:109], s[18:19], s48, v108, 0
	v_add3_u32 v109, v109, v159, v110
	v_lshl_add_u64 v[108:109], v[108:109], 1, v[146:147]
	v_mul_f32_e32 v110, v114, v144
	v_mul_f32_e32 v111, v115, v144
	v_mul_f32_e32 v114, v106, v144
	v_mul_f32_e32 v115, v107, v144
	v_mul_f32_e32 v106, v104, v144
	v_mul_f32_e32 v107, v105, v144
	v_cvt_pk_bf16_f32 v104, v112, v113
	v_cvt_pk_bf16_f32 v105, v110, v111
	v_mul_f32_e32 v84, v84, v144
	v_mul_f32_e32 v85, v85, v144
	v_cvt_pk_bf16_f32 v106, v106, v107
	v_cvt_pk_bf16_f32 v107, v114, v115
	global_store_dwordx4 v[108:109], v[104:107], off
	v_mul_f32_e32 v86, v86, v144
	v_mul_f32_e32 v87, v87, v144
	v_mul_f32_e32 v80, v80, v144
	v_mul_f32_e32 v81, v81, v144
	v_mul_f32_e32 v104, v94, v144
	v_mul_f32_e32 v105, v95, v144
	v_mul_f32_e32 v94, v92, v144
	v_mul_f32_e32 v95, v93, v144
	v_cvt_pk_bf16_f32 v92, v100, v101
	v_cvt_pk_bf16_f32 v93, v102, v103
	v_mul_f32_e32 v68, v68, v144
	v_mul_f32_e32 v69, v69, v144
	v_cvt_pk_bf16_f32 v94, v94, v95
	v_cvt_pk_bf16_f32 v95, v104, v105
	global_store_dwordx4 v[108:109], v[92:95], off offset:256
	v_mul_f32_e32 v70, v70, v144
	v_mul_f32_e32 v71, v71, v144
	v_mul_f32_e32 v62, v62, v144
	v_mul_f32_e32 v63, v63, v144
	v_or_b32_e32 v92, 32, v158
	v_mul_lo_u32 v94, s49, v92
	v_mad_u64_u32 v[92:93], s[18:19], s48, v92, 0
	v_add3_u32 v93, v93, v159, v94
	v_lshl_add_u64 v[92:93], v[92:93], 1, v[146:147]
	v_mul_f32_e32 v94, v98, v144
	v_mul_f32_e32 v95, v99, v144
	v_mul_f32_e32 v98, v90, v144
	v_mul_f32_e32 v99, v91, v144
	v_mul_f32_e32 v90, v88, v144
	v_mul_f32_e32 v91, v89, v144
	v_cvt_pk_bf16_f32 v88, v96, v97
	v_cvt_pk_bf16_f32 v89, v94, v95
	v_mul_f32_e32 v60, v60, v144
	v_mul_f32_e32 v61, v61, v144
	v_cvt_pk_bf16_f32 v90, v90, v91
	v_cvt_pk_bf16_f32 v91, v98, v99
	global_store_dwordx4 v[92:93], v[88:91], off
	v_mul_f32_e32 v52, v52, v144
	v_mul_f32_e32 v53, v53, v144
	v_mul_f32_e32 v54, v54, v144
	v_mul_f32_e32 v55, v55, v144
	v_mul_f32_e32 v88, v78, v144
	v_mul_f32_e32 v89, v79, v144
	v_mul_f32_e32 v78, v76, v144
	v_mul_f32_e32 v79, v77, v144
	v_cvt_pk_bf16_f32 v76, v84, v85
	v_cvt_pk_bf16_f32 v77, v86, v87
	v_mul_f32_e32 v46, v46, v144
	v_mul_f32_e32 v47, v47, v144
	v_cvt_pk_bf16_f32 v78, v78, v79
	v_cvt_pk_bf16_f32 v79, v88, v89
	global_store_dwordx4 v[92:93], v[76:79], off offset:256
	v_mul_f32_e32 v44, v44, v144
	v_mul_f32_e32 v45, v45, v144
	v_mul_f32_e32 v36, v36, v144
	v_mul_f32_e32 v37, v37, v144
	v_or_b32_e32 v76, 48, v158
	v_mul_lo_u32 v78, s49, v76
	v_mad_u64_u32 v[76:77], s[18:19], s48, v76, 0
	v_add3_u32 v77, v77, v159, v78
	v_lshl_add_u64 v[76:77], v[76:77], 1, v[146:147]
	v_mul_f32_e32 v78, v82, v144
	v_mul_f32_e32 v79, v83, v144
	v_mul_f32_e32 v82, v74, v144
	v_mul_f32_e32 v83, v75, v144
	v_mul_f32_e32 v74, v72, v144
	v_mul_f32_e32 v75, v73, v144
	v_cvt_pk_bf16_f32 v72, v80, v81
	v_cvt_pk_bf16_f32 v73, v78, v79
	v_mul_f32_e32 v38, v38, v144
	v_mul_f32_e32 v39, v39, v144
; __device__ __forceinline__ unsigned cvt_pk_bf16(float lo, float hi) { unsigned r; asm volatile("v_cvt_pk_bf16_f32 %0, %1, %2" : "=v"(r) : "v"(lo), "v"(hi)); return r; }
; #define PG8_BAR __builtin_amdgcn_s_barrier()
;     __device__ __forceinline__ void operator()(const f32x4 (&acc)[2][2][4][2], const Unit& u, int wr, int wc, int fr, int fq) const {
;     ...
;             for (int m = 0; m < 4; ++m) { bf16_t* rowp = base + (size_t)(row0 + ai * HALF + m * 16) * ldc + col0;
; #pragma unroll
;                 for (int bj = 0; bj < 2; ++bj) { f32x4 v0 = acc[ai][bj][m][0] * sc, v1 = acc[ai][bj][m][1] * sc;
;                     u32x4 w; w.x = cvt_pk_bf16(v0[0], v0[1]); w.y = cvt_pk_bf16(v0[2], v0[3]); w.z = cvt_pk_bf16(v1[0], v1[1]); w.w = cvt_pk_bf16(v1[2], v1[3]);
;                     *(u32x4*)(rowp + bj * HALF) = w; } }
; template <class Epi, class Sched, bool ALIGN_EPI = false, bool SP2 = false>
; __device__ __forceinline__ void gemm_phase(PG8_LAS unsigned char* lds, const Gemm g, const Sched& S, const Epi& E) {
;     ...
;         if (!has_next) break;
; #pragma unroll
;         for (int a = 0; a < 2; ++a)
; #pragma unroll
;             for (int b = 0; b < 2; ++b)
; #pragma unroll
;                 for (int m = 0; m < 4; ++m)
; #pragma unroll
;                     for (int n = 0; n < 2; ++n) acc[a][b][m][n] = (f32x4){0.f, 0.f, 0.f, 0.f};
;         cur = nxt; cA = nA; cB = nB; ++ui;
;         if constexpr (ALIGN_EPI) { if (wr == 1) PG8_BAR; }
	v_cvt_pk_bf16_f32 v74, v74, v75
	v_cvt_pk_bf16_f32 v75, v82, v83
	global_store_dwordx4 v[76:77], v[72:75], off
	v_mul_f32_e32 v30, v30, v144
	v_mul_f32_e32 v31, v31, v144
	v_mul_f32_e32 v28, v28, v144
	v_mul_f32_e32 v29, v29, v144
	v_mul_f32_e32 v72, v66, v144
	v_mul_f32_e32 v73, v67, v144
	v_mul_f32_e32 v66, v64, v144
	v_mul_f32_e32 v67, v65, v144
	v_cvt_pk_bf16_f32 v64, v68, v69
	v_cvt_pk_bf16_f32 v65, v70, v71
	v_mul_f32_e32 v20, v20, v144
	v_mul_f32_e32 v21, v21, v144
	v_cvt_pk_bf16_f32 v66, v66, v67
	v_cvt_pk_bf16_f32 v67, v72, v73
	global_store_dwordx4 v[76:77], v[64:67], off offset:256
	v_mul_f32_e32 v22, v22, v144
	v_mul_f32_e32 v23, v23, v144
	v_mul_f32_e32 v14, v14, v144
	v_mul_f32_e32 v15, v15, v144
	v_add_u32_e32 v64, 0x80, v158
	v_ashrrev_i32_e32 v65, 31, v64
	v_mul_lo_u32 v66, s48, v65
	v_mul_lo_u32 v67, s49, v64
	v_mad_u64_u32 v[64:65], s[18:19], s48, v64, 0
	v_add3_u32 v65, v65, v66, v67
	v_lshl_add_u64 v[64:65], v[64:65], 1, v[146:147]
	v_mul_f32_e32 v66, v58, v144
	v_mul_f32_e32 v67, v59, v144
	v_mul_f32_e32 v58, v56, v144
	v_mul_f32_e32 v59, v57, v144
	v_cvt_pk_bf16_f32 v56, v60, v61
	v_cvt_pk_bf16_f32 v57, v62, v63
	v_mul_f32_e32 v12, v12, v144
	v_mul_f32_e32 v13, v13, v144
	v_cvt_pk_bf16_f32 v58, v58, v59
	v_cvt_pk_bf16_f32 v59, v66, v67
	global_store_dwordx4 v[64:65], v[56:59], off
	s_andn2_b64 vcc, exec, s[4:5]
	s_mov_b64 s[4:5], -1
	v_mul_f32_e32 v56, v50, v144
	v_mul_f32_e32 v57, v51, v144
	v_mul_f32_e32 v50, v48, v144
	v_mul_f32_e32 v51, v49, v144
	v_cvt_pk_bf16_f32 v48, v52, v53
	v_cvt_pk_bf16_f32 v49, v54, v55
	v_mul_f32_e32 v6, v6, v144
	v_mul_f32_e32 v7, v7, v144
	v_cvt_pk_bf16_f32 v50, v50, v51
	v_cvt_pk_bf16_f32 v51, v56, v57
	global_store_dwordx4 v[64:65], v[48:51], off offset:256
	v_mul_f32_e32 v4, v4, v144
	v_mul_f32_e32 v5, v5, v144
	s_nop 0
	v_add_u32_e32 v48, 0x90, v158
	v_ashrrev_i32_e32 v49, 31, v48
	v_mul_lo_u32 v50, s48, v49
	v_mul_lo_u32 v51, s49, v48
	v_mad_u64_u32 v[48:49], s[18:19], s48, v48, 0
	v_add3_u32 v49, v49, v50, v51
	v_lshl_add_u64 v[48:49], v[48:49], 1, v[146:147]
	v_mul_f32_e32 v50, v42, v144
	v_mul_f32_e32 v51, v43, v144
	v_mul_f32_e32 v42, v40, v144
	v_mul_f32_e32 v43, v41, v144
	v_cvt_pk_bf16_f32 v40, v44, v45
	v_cvt_pk_bf16_f32 v41, v46, v47
	s_nop 0
	v_cvt_pk_bf16_f32 v42, v42, v43
	v_cvt_pk_bf16_f32 v43, v50, v51
	global_store_dwordx4 v[48:49], v[40:43], off
	s_nop 1
	v_mul_f32_e32 v40, v34, v144
	v_mul_f32_e32 v41, v35, v144
	v_mul_f32_e32 v34, v32, v144
	v_mul_f32_e32 v35, v33, v144
	v_cvt_pk_bf16_f32 v32, v36, v37
	v_cvt_pk_bf16_f32 v33, v38, v39
	s_nop 0
	v_cvt_pk_bf16_f32 v34, v34, v35
	v_cvt_pk_bf16_f32 v35, v40, v41
	global_store_dwordx4 v[48:49], v[32:35], off offset:256
	s_nop 1
	v_add_u32_e32 v32, 0xa0, v158
	v_ashrrev_i32_e32 v33, 31, v32
	v_mul_lo_u32 v34, s48, v33
	v_mul_lo_u32 v35, s49, v32
	v_mad_u64_u32 v[32:33], s[18:19], s48, v32, 0
	v_add3_u32 v33, v33, v34, v35
	v_lshl_add_u64 v[32:33], v[32:33], 1, v[146:147]
	v_mul_f32_e32 v34, v26, v144
	v_mul_f32_e32 v35, v27, v144
	v_mul_f32_e32 v26, v24, v144
	v_mul_f32_e32 v27, v25, v144
	v_cvt_pk_bf16_f32 v24, v28, v29
	v_cvt_pk_bf16_f32 v25, v30, v31
	s_nop 0
	v_cvt_pk_bf16_f32 v26, v26, v27
	v_cvt_pk_bf16_f32 v27, v34, v35
	global_store_dwordx4 v[32:33], v[24:27], off
	s_nop 1
	v_mul_f32_e32 v24, v18, v144
	v_mul_f32_e32 v25, v19, v144
	v_mul_f32_e32 v18, v16, v144
	v_mul_f32_e32 v19, v17, v144
	v_cvt_pk_bf16_f32 v16, v20, v21
	v_cvt_pk_bf16_f32 v17, v22, v23
	s_nop 0
	v_cvt_pk_bf16_f32 v18, v18, v19
	v_cvt_pk_bf16_f32 v19, v24, v25
	global_store_dwordx4 v[32:33], v[16:19], off offset:256
	s_nop 1
	v_add_u32_e32 v16, 0xb0, v158
	v_ashrrev_i32_e32 v17, 31, v16
	v_mul_lo_u32 v18, s48, v17
	v_mul_lo_u32 v19, s49, v16
	v_mad_u64_u32 v[16:17], s[18:19], s48, v16, 0
	v_add3_u32 v17, v17, v18, v19
	v_lshl_add_u64 v[16:17], v[16:17], 1, v[146:147]
	v_mul_f32_e32 v18, v10, v144
	v_mul_f32_e32 v19, v11, v144
	v_mul_f32_e32 v10, v8, v144
	v_mul_f32_e32 v11, v9, v144
	v_cvt_pk_bf16_f32 v8, v12, v13
	v_cvt_pk_bf16_f32 v9, v14, v15
	s_nop 0
	v_cvt_pk_bf16_f32 v10, v10, v11
	v_cvt_pk_bf16_f32 v11, v18, v19
	global_store_dwordx4 v[16:17], v[8:11], off
	s_nop 1
	v_mul_f32_e32 v8, v2, v144
	v_mul_f32_e32 v9, v3, v144
	v_mul_f32_e32 v2, v0, v144
	v_mul_f32_e32 v3, v1, v144
	v_cvt_pk_bf16_f32 v0, v4, v5
	v_cvt_pk_bf16_f32 v1, v6, v7
	s_nop 0
	v_cvt_pk_bf16_f32 v2, v2, v3
	v_cvt_pk_bf16_f32 v3, v8, v9
	global_store_dwordx4 v[16:17], v[0:3], off offset:256
	s_cbranch_vccnz .LBB0_44
	s_andn2_b64 vcc, exec, s[8:9]
	s_cbranch_vccnz .LBB0_43
	s_barrier
	s_branch .LBB0_43

; __device__ __forceinline__ unsigned cvt_pk_bf16(float lo, float hi) { unsigned r; asm volatile("v_cvt_pk_bf16_f32 %0, %1, %2" : "=v"(r) : "v"(lo), "v"(hi)); return r; }
;     __device__ __forceinline__ void operator()(const f32x4 (&acc)[2][2][4][2], const Unit& u, int wr, int wc, int fr, int fq) const {
;     ...
;             for (int m = 0; m < 4; ++m) { const int row = u.pm * BM + ai * HALF + wr * 64 + m * 16 + fr;
;                 const float* xr = (row < 32768 ? xp + (size_t)row * 2048 : xs + (size_t)(row - 32768) * 2048) + col0; bf16_t* zrow = zb + (size_t)row * 2048 + col0;
;                 float s = 0.f;
; #pragma unroll
;                 for (int bj = 0; bj < 2; ++bj) { const f32x4 v0 = *(const f32x4*)(xr + bj * HALF) + acc[ai][bj][m][0], v1 = *(const f32x4*)(xr + bj * HALF + 4) + acc[ai][bj][m][1];
;                     s += ((v0[0] * v0[0] + v0[1] * v0[1]) + (v0[2] * v0[2] + v0[3] * v0[3])) + ((v1[0] * v1[0] + v1[1] * v1[1]) + (v1[2] * v1[2] + v1[3] * v1[3]));
;                     u32x4 w; w.x = cvt_pk_bf16(v0[0], v0[1]); w.y = cvt_pk_bf16(v0[2], v0[3]); w.z = cvt_pk_bf16(v1[0], v1[1]); w.w = cvt_pk_bf16(v1[2], v1[3]);
;                     *(u32x4*)(zrow + bj * HALF) = w; }
;                 s += __shfl_xor(s, 16); s += __shfl_xor(s, 32);
;                 if (fq == 0) part[(size_t)row * 32 + u.pn * 4 + wc] = s; }
.LBB0_254:
	v_lshl_add_u32 v146, s44, 8, v152
	v_cmp_lt_i32_e32 vcc, s69, v146
	s_and_saveexec_b64 s[18:19], vcc
	s_xor_b64 s[44:45], exec, s[18:19]
	v_add_u32_e32 v136, 0xffff8000, v146
	v_lshlrev_b64 v[148:149], 13, v[136:137]
	v_lshl_add_u64 v[150:151], s[14:15], 0, v[148:149]
	v_mov_b32_e32 v147, v137
	s_andn2_saveexec_b64 s[44:45], s[44:45]
	v_ashrrev_i32_e32 v147, 31, v146
	v_lshlrev_b64 v[148:149], 13, v[146:147]
	v_lshl_add_u64 v[150:151], s[12:13], 0, v[148:149]
	s_or_b64 exec, exec, s[44:45]
	v_lshl_or_b32 v148, s8, 8, v154
	v_ashrrev_i32_e32 v149, 31, v148
	v_lshl_add_u64 v[150:151], v[148:149], 2, v[150:151]
	global_load_dwordx4 v[160:163], v[150:151], off
	global_load_dwordx4 v[164:167], v[150:151], off offset:16
	v_lshlrev_b64 v[168:169], 12, v[146:147]
	v_lshl_add_u64 v[168:169], s[16:17], 0, v[168:169]
	v_lshl_add_u64 v[168:169], v[148:149], 1, v[168:169]
	v_xor_b32_e32 v136, 32, v158
	s_lshl_b32 s44, s8, 2
	s_ashr_i32 s45, s44, 31
	s_waitcnt vmcnt(0)
	v_add_f32_e32 v126, v126, v162
	v_add_f32_e32 v127, v127, v163
	v_add_f32_e32 v170, v124, v160
	v_add_f32_e32 v171, v125, v161
	v_add_f32_e32 v166, v122, v166
	v_add_f32_e32 v167, v123, v167
	v_add_f32_e32 v164, v120, v164
	v_add_f32_e32 v165, v121, v165
	v_cvt_pk_bf16_f32 v120, v170, v171
	v_cvt_pk_bf16_f32 v121, v126, v127
	v_mul_f32_e32 v127, v127, v127
	v_cvt_pk_bf16_f32 v122, v164, v165
	v_cvt_pk_bf16_f32 v123, v166, v167
	global_store_dwordx4 v[168:169], v[120:123], off
	global_load_dwordx4 v[122:125], v[150:151], off offset:512
	s_nop 0
	global_load_dwordx4 v[160:163], v[150:151], off offset:528
	v_and_b32_e32 v121, 64, v158
	v_mul_f32_e32 v150, v171, v171
	v_mul_f32_e32 v151, v165, v165
	v_mul_f32_e32 v159, v167, v167
	v_xor_b32_e32 v120, 16, v158
	v_add_u32_e32 v121, 64, v121
	v_fmac_f32_e32 v150, v170, v170
	v_fmac_f32_e32 v127, v126, v126
	v_fmac_f32_e32 v151, v164, v164
	v_fmac_f32_e32 v159, v166, v166
	v_cmp_lt_i32_e32 vcc, v120, v121
	v_add_f32_e32 v126, v150, v127
	v_add_f32_e32 v127, v151, v159
	v_cndmask_b32_e32 v120, v158, v120, vcc
	v_add_f32_e32 v126, v126, v127
	v_lshlrev_b32_e32 v120, 2, v120
	v_cmp_lt_i32_e32 vcc, v136, v121
	s_waitcnt vmcnt(1)
	v_add_f32_e32 v118, v118, v124
	v_add_f32_e32 v119, v119, v125
	v_add_f32_e32 v116, v116, v122
	v_add_f32_e32 v117, v117, v123
	s_waitcnt vmcnt(0)
	v_add_f32_e32 v114, v114, v162
	v_add_f32_e32 v115, v115, v163
	v_add_f32_e32 v124, v112, v160
	v_add_f32_e32 v125, v113, v161
	v_mul_f32_e32 v112, v117, v117
	v_mul_f32_e32 v113, v119, v119
	v_mul_f32_e32 v122, v125, v125
	v_mul_f32_e32 v123, v115, v115
	v_fmac_f32_e32 v112, v116, v116
	v_fmac_f32_e32 v113, v118, v118
	v_fmac_f32_e32 v122, v124, v124
	v_fmac_f32_e32 v123, v114, v114
	v_add_f32_e32 v112, v112, v113
	v_add_f32_e32 v113, v122, v123
	v_add_f32_e32 v112, v112, v113
	v_add_f32_e32 v112, v126, v112
	ds_bpermute_b32 v113, v120, v112
	v_cndmask_b32_e32 v121, v158, v136, vcc
	v_cvt_pk_bf16_f32 v122, v116, v117
	v_lshlrev_b32_e32 v116, 2, v121
	v_cvt_pk_bf16_f32 v123, v118, v119
	s_waitcnt lgkmcnt(0)
	v_add_f32_e32 v112, v112, v113
	ds_bpermute_b32 v113, v116, v112
	v_cvt_pk_bf16_f32 v124, v124, v125
	v_cvt_pk_bf16_f32 v125, v114, v115
	global_store_dwordx4 v[168:169], v[122:125], off offset:256
	s_and_saveexec_b64 s[46:47], s[6:7]
	s_cbranch_execz .LBB0_260
	v_lshlrev_b64 v[114:115], 7, v[146:147]
	v_lshl_add_u64 v[114:115], s[22:23], 0, v[114:115]
	v_lshl_add_u64 v[114:115], s[44:45], 2, v[114:115]
	s_lshl_b32 s8, s57, 2
	v_lshl_add_u64 v[114:115], v[114:115], 0, s[8:9]
	s_waitcnt lgkmcnt(0)
	v_add_f32_e32 v112, v112, v113
	global_store_dword v[114:115], v112, off
.LBB0_260:
	s_or_b64 exec, exec, s[46:47]
	s_waitcnt lgkmcnt(0)
	v_or_b32_e32 v112, 16, v146
	v_cmp_lt_i32_e32 vcc, s69, v112
	s_and_saveexec_b64 s[18:19], vcc
	s_xor_b64 s[46:47], exec, s[18:19]
	v_add_u32_e32 v136, 0xffff8010, v146
	v_lshlrev_b64 v[114:115], 13, v[136:137]
	v_lshl_add_u64 v[114:115], s[14:15], 0, v[114:115]
	v_mov_b32_e32 v113, v137
	s_andn2_saveexec_b64 s[46:47], s[46:47]
	v_ashrrev_i32_e32 v113, 31, v112
	v_lshlrev_b64 v[114:115], 13, v[112:113]
	v_lshl_add_u64 v[114:115], s[12:13], 0, v[114:115]
	s_or_b64 exec, exec, s[46:47]
	v_lshl_add_u64 v[114:115], v[148:149], 2, v[114:115]
	global_load_dwordx4 v[122:125], v[114:115], off
	global_load_dwordx4 v[160:163], v[114:115], off offset:16
	v_lshlrev_b64 v[118:119], 12, v[112:113]
	v_lshl_add_u64 v[118:119], s[16:17], 0, v[118:119]
	v_lshl_add_u64 v[118:119], v[148:149], 1, v[118:119]
	s_waitcnt vmcnt(1)
	v_add_f32_e32 v124, v110, v124
	v_add_f32_e32 v125, v111, v125
	v_add_f32_e32 v122, v108, v122
	v_add_f32_e32 v123, v109, v123
	s_waitcnt vmcnt(0)
	v_add_f32_e32 v126, v106, v162
	v_add_f32_e32 v127, v107, v163
	v_add_f32_e32 v150, v104, v160
	v_add_f32_e32 v151, v105, v161
	v_cvt_pk_bf16_f32 v104, v122, v123
	v_cvt_pk_bf16_f32 v105, v124, v125
	v_mul_f32_e32 v121, v127, v127
	v_cvt_pk_bf16_f32 v106, v150, v151
	v_cvt_pk_bf16_f32 v107, v126, v127
	global_store_dwordx4 v[118:119], v[104:107], off
	global_load_dwordx4 v[104:107], v[114:115], off offset:512
	s_nop 0
	global_load_dwordx4 v[108:111], v[114:115], off offset:528
	v_mul_f32_e32 v114, v123, v123
	v_mul_f32_e32 v115, v125, v125
	v_mul_f32_e32 v117, v151, v151
	v_fmac_f32_e32 v114, v122, v122
	v_fmac_f32_e32 v115, v124, v124
	v_fmac_f32_e32 v117, v150, v150
	v_fmac_f32_e32 v121, v126, v126
	v_add_f32_e32 v114, v114, v115
	v_add_f32_e32 v115, v117, v121
	v_add_f32_e32 v114, v114, v115
	s_waitcnt vmcnt(1)
	v_add_f32_e32 v102, v102, v106
	v_add_f32_e32 v103, v103, v107
	v_add_f32_e32 v100, v100, v104
	v_add_f32_e32 v101, v101, v105
	s_waitcnt vmcnt(0)
	v_add_f32_e32 v104, v98, v110
	v_add_f32_e32 v105, v99, v111
	v_add_f32_e32 v106, v96, v108
	v_add_f32_e32 v107, v97, v109
	v_mul_f32_e32 v96, v101, v101
	v_mul_f32_e32 v97, v103, v103
	v_mul_f32_e32 v98, v107, v107
	v_mul_f32_e32 v99, v105, v105
	v_fmac_f32_e32 v96, v100, v100
	v_fmac_f32_e32 v97, v102, v102
	v_fmac_f32_e32 v98, v106, v106
	v_fmac_f32_e32 v99, v104, v104
	v_add_f32_e32 v96, v96, v97
	v_add_f32_e32 v97, v98, v99
	v_add_f32_e32 v96, v96, v97
	v_add_f32_e32 v96, v114, v96
	ds_bpermute_b32 v97, v120, v96
	v_cvt_pk_bf16_f32 v98, v100, v101
	v_cvt_pk_bf16_f32 v99, v102, v103
	v_cvt_pk_bf16_f32 v100, v106, v107
	v_cvt_pk_bf16_f32 v101, v104, v105
	s_waitcnt lgkmcnt(0)
	v_add_f32_e32 v96, v96, v97
	ds_bpermute_b32 v97, v116, v96
	global_store_dwordx4 v[118:119], v[98:101], off offset:256
	s_and_saveexec_b64 s[46:47], s[6:7]
	s_cbranch_execz .LBB0_266
	v_lshlrev_b64 v[98:99], 7, v[112:113]
	v_lshl_add_u64 v[98:99], s[22:23], 0, v[98:99]
	v_lshl_add_u64 v[98:99], s[44:45], 2, v[98:99]
	s_lshl_b32 s8, s57, 2
	v_lshl_add_u64 v[98:99], v[98:99], 0, s[8:9]
	s_waitcnt lgkmcnt(0)
	v_add_f32_e32 v96, v96, v97
	global_store_dword v[98:99], v96, off
; __device__ __forceinline__ unsigned cvt_pk_bf16(float lo, float hi) { unsigned r; asm volatile("v_cvt_pk_bf16_f32 %0, %1, %2" : "=v"(r) : "v"(lo), "v"(hi)); return r; }
;     __device__ __forceinline__ void operator()(const f32x4 (&acc)[2][2][4][2], const Unit& u, int wr, int wc, int fr, int fq) const {
;     ...
;             for (int m = 0; m < 4; ++m) { const int row = u.pm * BM + ai * HALF + wr * 64 + m * 16 + fr;
;                 const float* xr = (row < 32768 ? xp + (size_t)row * 2048 : xs + (size_t)(row - 32768) * 2048) + col0; bf16_t* zrow = zb + (size_t)row * 2048 + col0;
;                 float s = 0.f;
; #pragma unroll
;                 for (int bj = 0; bj < 2; ++bj) { const f32x4 v0 = *(const f32x4*)(xr + bj * HALF) + acc[ai][bj][m][0], v1 = *(const f32x4*)(xr + bj * HALF + 4) + acc[ai][bj][m][1];
;                     s += ((v0[0] * v0[0] + v0[1] * v0[1]) + (v0[2] * v0[2] + v0[3] * v0[3])) + ((v1[0] * v1[0] + v1[1] * v1[1]) + (v1[2] * v1[2] + v1[3] * v1[3]));
;                     u32x4 w; w.x = cvt_pk_bf16(v0[0], v0[1]); w.y = cvt_pk_bf16(v0[2], v0[3]); w.z = cvt_pk_bf16(v1[0], v1[1]); w.w = cvt_pk_bf16(v1[2], v1[3]);
;                     *(u32x4*)(zrow + bj * HALF) = w; }
;                 s += __shfl_xor(s, 16); s += __shfl_xor(s, 32);
;                 if (fq == 0) part[(size_t)row * 32 + u.pn * 4 + wc] = s; }
.LBB0_266:
	s_or_b64 exec, exec, s[46:47]
	s_waitcnt lgkmcnt(0)
	v_or_b32_e32 v96, 32, v146
	v_cmp_lt_i32_e32 vcc, s69, v96
	s_and_saveexec_b64 s[18:19], vcc
	s_xor_b64 s[46:47], exec, s[18:19]
	v_add_u32_e32 v136, 0xffff8020, v146
	v_lshlrev_b64 v[98:99], 13, v[136:137]
	v_lshl_add_u64 v[98:99], s[14:15], 0, v[98:99]
	v_mov_b32_e32 v97, v137
	s_andn2_saveexec_b64 s[46:47], s[46:47]
	v_ashrrev_i32_e32 v97, 31, v96
	v_lshlrev_b64 v[98:99], 13, v[96:97]
	v_lshl_add_u64 v[98:99], s[12:13], 0, v[98:99]
	s_or_b64 exec, exec, s[46:47]
	v_lshl_add_u64 v[106:107], v[148:149], 2, v[98:99]
	global_load_dwordx4 v[98:101], v[106:107], off
	global_load_dwordx4 v[102:105], v[106:107], off offset:16
	v_lshlrev_b64 v[108:109], 12, v[96:97]
	v_lshl_add_u64 v[108:109], s[16:17], 0, v[108:109]
	v_lshl_add_u64 v[108:109], v[148:149], 1, v[108:109]
	s_waitcnt vmcnt(1)
	v_add_f32_e32 v100, v94, v100
	v_add_f32_e32 v101, v95, v101
	v_add_f32_e32 v98, v92, v98
	v_add_f32_e32 v99, v93, v99
	s_waitcnt vmcnt(0)
	v_add_f32_e32 v104, v90, v104
	v_add_f32_e32 v105, v91, v105
	v_add_f32_e32 v102, v88, v102
	v_add_f32_e32 v103, v89, v103
	v_cvt_pk_bf16_f32 v88, v98, v99
	v_cvt_pk_bf16_f32 v89, v100, v101
	v_mul_f32_e32 v99, v99, v99
	v_cvt_pk_bf16_f32 v90, v102, v103
	v_cvt_pk_bf16_f32 v91, v104, v105
	global_store_dwordx4 v[108:109], v[88:91], off
	global_load_dwordx4 v[88:91], v[106:107], off offset:512
	s_nop 0
	global_load_dwordx4 v[92:95], v[106:107], off offset:528
	v_mul_f32_e32 v101, v101, v101
	v_mul_f32_e32 v103, v103, v103
	v_mul_f32_e32 v105, v105, v105
	v_fmac_f32_e32 v99, v98, v98
	v_fmac_f32_e32 v101, v100, v100
	v_fmac_f32_e32 v103, v102, v102
	v_fmac_f32_e32 v105, v104, v104
	v_add_f32_e32 v98, v99, v101
	v_add_f32_e32 v99, v103, v105
	v_add_f32_e32 v98, v98, v99
	s_waitcnt vmcnt(1)
	v_add_f32_e32 v86, v86, v90
	v_add_f32_e32 v87, v87, v91
	v_add_f32_e32 v84, v84, v88
	v_add_f32_e32 v85, v85, v89
	s_waitcnt vmcnt(0)
	v_add_f32_e32 v88, v82, v94
	v_add_f32_e32 v89, v83, v95
	v_add_f32_e32 v90, v80, v92
	v_add_f32_e32 v91, v81, v93
	v_mul_f32_e32 v80, v85, v85
	v_mul_f32_e32 v81, v87, v87
	v_mul_f32_e32 v82, v91, v91
	v_mul_f32_e32 v83, v89, v89
	v_fmac_f32_e32 v80, v84, v84
	v_fmac_f32_e32 v81, v86, v86
	v_fmac_f32_e32 v82, v90, v90
	v_fmac_f32_e32 v83, v88, v88
	v_add_f32_e32 v80, v80, v81
	v_add_f32_e32 v81, v82, v83
	v_add_f32_e32 v80, v80, v81
	v_add_f32_e32 v80, v98, v80
	ds_bpermute_b32 v81, v120, v80
	v_cvt_pk_bf16_f32 v82, v84, v85
	v_cvt_pk_bf16_f32 v83, v86, v87
	v_cvt_pk_bf16_f32 v84, v90, v91
	v_cvt_pk_bf16_f32 v85, v88, v89
	s_waitcnt lgkmcnt(0)
	v_add_f32_e32 v80, v80, v81
	ds_bpermute_b32 v81, v116, v80
	global_store_dwordx4 v[108:109], v[82:85], off offset:256
	s_and_saveexec_b64 s[46:47], s[6:7]
	s_cbranch_execz .LBB0_272
	v_lshlrev_b64 v[82:83], 7, v[96:97]
	v_lshl_add_u64 v[82:83], s[22:23], 0, v[82:83]
	v_lshl_add_u64 v[82:83], s[44:45], 2, v[82:83]
	s_lshl_b32 s8, s57, 2
	v_lshl_add_u64 v[82:83], v[82:83], 0, s[8:9]
	s_waitcnt lgkmcnt(0)
	v_add_f32_e32 v80, v80, v81
	global_store_dword v[82:83], v80, off
.LBB0_272:
	s_or_b64 exec, exec, s[46:47]
	s_waitcnt lgkmcnt(0)
	v_or_b32_e32 v80, 48, v146
	v_cmp_lt_i32_e32 vcc, s69, v80
	s_and_saveexec_b64 s[18:19], vcc
	s_xor_b64 s[46:47], exec, s[18:19]
	v_add_u32_e32 v136, 0xffff8030, v146
	v_lshlrev_b64 v[82:83], 13, v[136:137]
	v_lshl_add_u64 v[82:83], s[14:15], 0, v[82:83]
	v_mov_b32_e32 v81, v137
	s_andn2_saveexec_b64 s[46:47], s[46:47]
	v_ashrrev_i32_e32 v81, 31, v80
	v_lshlrev_b64 v[82:83], 13, v[80:81]
	v_lshl_add_u64 v[82:83], s[12:13], 0, v[82:83]
	s_or_b64 exec, exec, s[46:47]
	v_lshl_add_u64 v[90:91], v[148:149], 2, v[82:83]
	global_load_dwordx4 v[82:85], v[90:91], off
	global_load_dwordx4 v[86:89], v[90:91], off offset:16
	v_lshlrev_b64 v[92:93], 12, v[80:81]
	v_lshl_add_u64 v[92:93], s[16:17], 0, v[92:93]
	v_lshl_add_u64 v[92:93], v[148:149], 1, v[92:93]
	s_waitcnt vmcnt(1)
	v_add_f32_e32 v84, v78, v84
	v_add_f32_e32 v85, v79, v85
	v_add_f32_e32 v82, v76, v82
	v_add_f32_e32 v83, v77, v83
	s_waitcnt vmcnt(0)
	v_add_f32_e32 v88, v74, v88
	v_add_f32_e32 v89, v75, v89
	v_add_f32_e32 v86, v72, v86
	v_add_f32_e32 v87, v73, v87
	v_cvt_pk_bf16_f32 v72, v82, v83
	v_cvt_pk_bf16_f32 v73, v84, v85
	v_mul_f32_e32 v83, v83, v83
	v_cvt_pk_bf16_f32 v74, v86, v87
	v_cvt_pk_bf16_f32 v75, v88, v89
	global_store_dwordx4 v[92:93], v[72:75], off
	global_load_dwordx4 v[72:75], v[90:91], off offset:512
	s_nop 0
	global_load_dwordx4 v[76:79], v[90:91], off offset:528
	v_mul_f32_e32 v85, v85, v85
	v_mul_f32_e32 v87, v87, v87
	v_mul_f32_e32 v89, v89, v89
	v_fmac_f32_e32 v83, v82, v82
	v_fmac_f32_e32 v85, v84, v84
	v_fmac_f32_e32 v87, v86, v86
	v_fmac_f32_e32 v89, v88, v88
	v_add_f32_e32 v82, v83, v85
	v_add_f32_e32 v83, v87, v89
	v_add_f32_e32 v82, v82, v83
	s_waitcnt vmcnt(1)
	v_add_f32_e32 v70, v70, v74
	v_add_f32_e32 v71, v71, v75
	v_add_f32_e32 v68, v68, v72
	v_add_f32_e32 v69, v69, v73
	s_waitcnt vmcnt(0)
	v_add_f32_e32 v72, v66, v78
	v_add_f32_e32 v73, v67, v79
	v_add_f32_e32 v74, v64, v76
	v_add_f32_e32 v75, v65, v77
	v_mul_f32_e32 v64, v69, v69
	v_mul_f32_e32 v65, v71, v71
	v_mul_f32_e32 v66, v75, v75
	v_mul_f32_e32 v67, v73, v73
	v_fmac_f32_e32 v64, v68, v68
	v_fmac_f32_e32 v65, v70, v70
	v_fmac_f32_e32 v66, v74, v74
	v_fmac_f32_e32 v67, v72, v72
	v_add_f32_e32 v64, v64, v65
	v_add_f32_e32 v65, v66, v67
	v_add_f32_e32 v64, v64, v65
	v_add_f32_e32 v64, v82, v64
	ds_bpermute_b32 v65, v120, v64
	v_cvt_pk_bf16_f32 v66, v68, v69
	v_cvt_pk_bf16_f32 v67, v70, v71
	v_cvt_pk_bf16_f32 v68, v74, v75
	v_cvt_pk_bf16_f32 v69, v72, v73
	s_waitcnt lgkmcnt(0)
	v_add_f32_e32 v64, v64, v65
	ds_bpermute_b32 v65, v116, v64
	global_store_dwordx4 v[92:93], v[66:69], off offset:256
	s_and_saveexec_b64 s[46:47], s[6:7]
	s_cbranch_execz .LBB0_278
	v_lshlrev_b64 v[66:67], 7, v[80:81]
	v_lshl_add_u64 v[66:67], s[22:23], 0, v[66:67]
	v_lshl_add_u64 v[66:67], s[44:45], 2, v[66:67]
	s_lshl_b32 s8, s57, 2
	v_lshl_add_u64 v[66:67], v[66:67], 0, s[8:9]
	s_waitcnt lgkmcnt(0)
	v_add_f32_e32 v64, v64, v65
	global_store_dword v[66:67], v64, off
; __device__ __forceinline__ unsigned cvt_pk_bf16(float lo, float hi) { unsigned r; asm volatile("v_cvt_pk_bf16_f32 %0, %1, %2" : "=v"(r) : "v"(lo), "v"(hi)); return r; }
;     __device__ __forceinline__ void operator()(const f32x4 (&acc)[2][2][4][2], const Unit& u, int wr, int wc, int fr, int fq) const {
;     ...
;             for (int m = 0; m < 4; ++m) { const int row = u.pm * BM + ai * HALF + wr * 64 + m * 16 + fr;
;                 const float* xr = (row < 32768 ? xp + (size_t)row * 2048 : xs + (size_t)(row - 32768) * 2048) + col0; bf16_t* zrow = zb + (size_t)row * 2048 + col0;
;                 float s = 0.f;
; #pragma unroll
;                 for (int bj = 0; bj < 2; ++bj) { const f32x4 v0 = *(const f32x4*)(xr + bj * HALF) + acc[ai][bj][m][0], v1 = *(const f32x4*)(xr + bj * HALF + 4) + acc[ai][bj][m][1];
;                     s += ((v0[0] * v0[0] + v0[1] * v0[1]) + (v0[2] * v0[2] + v0[3] * v0[3])) + ((v1[0] * v1[0] + v1[1] * v1[1]) + (v1[2] * v1[2] + v1[3] * v1[3]));
;                     u32x4 w; w.x = cvt_pk_bf16(v0[0], v0[1]); w.y = cvt_pk_bf16(v0[2], v0[3]); w.z = cvt_pk_bf16(v1[0], v1[1]); w.w = cvt_pk_bf16(v1[2], v1[3]);
;                     *(u32x4*)(zrow + bj * HALF) = w; }
;                 s += __shfl_xor(s, 16); s += __shfl_xor(s, 32);
;                 if (fq == 0) part[(size_t)row * 32 + u.pn * 4 + wc] = s; }
.LBB0_278:
	s_or_b64 exec, exec, s[46:47]
	s_waitcnt lgkmcnt(0)
	v_add_u32_e32 v64, 0x80, v146
	v_cmp_lt_i32_e32 vcc, s69, v64
	s_and_saveexec_b64 s[18:19], vcc
	s_xor_b64 s[46:47], exec, s[18:19]
	v_add_u32_e32 v136, 0xffff8080, v146
	v_lshlrev_b64 v[66:67], 13, v[136:137]
	v_lshl_add_u64 v[66:67], s[14:15], 0, v[66:67]
	v_mov_b32_e32 v65, v137
	s_andn2_saveexec_b64 s[46:47], s[46:47]
	v_ashrrev_i32_e32 v65, 31, v64
	v_lshlrev_b64 v[66:67], 13, v[64:65]
	v_lshl_add_u64 v[66:67], s[12:13], 0, v[66:67]
	s_or_b64 exec, exec, s[46:47]
	v_lshl_add_u64 v[74:75], v[148:149], 2, v[66:67]
	global_load_dwordx4 v[66:69], v[74:75], off
	global_load_dwordx4 v[70:73], v[74:75], off offset:16
	v_lshlrev_b64 v[76:77], 12, v[64:65]
	v_lshl_add_u64 v[76:77], s[16:17], 0, v[76:77]
	v_lshl_add_u64 v[76:77], v[148:149], 1, v[76:77]
	s_waitcnt vmcnt(1)
	v_add_f32_e32 v68, v62, v68
	v_add_f32_e32 v69, v63, v69
	v_add_f32_e32 v66, v60, v66
	v_add_f32_e32 v67, v61, v67
	s_waitcnt vmcnt(0)
	v_add_f32_e32 v72, v58, v72
	v_add_f32_e32 v73, v59, v73
	v_add_f32_e32 v70, v56, v70
	v_add_f32_e32 v71, v57, v71
	v_cvt_pk_bf16_f32 v56, v66, v67
	v_cvt_pk_bf16_f32 v57, v68, v69
	v_mul_f32_e32 v67, v67, v67
	v_cvt_pk_bf16_f32 v58, v70, v71
	v_cvt_pk_bf16_f32 v59, v72, v73
	global_store_dwordx4 v[76:77], v[56:59], off
	global_load_dwordx4 v[56:59], v[74:75], off offset:512
	s_nop 0
	global_load_dwordx4 v[60:63], v[74:75], off offset:528
	v_mul_f32_e32 v69, v69, v69
	v_mul_f32_e32 v71, v71, v71
	v_mul_f32_e32 v73, v73, v73
	v_fmac_f32_e32 v67, v66, v66
	v_fmac_f32_e32 v69, v68, v68
	v_fmac_f32_e32 v71, v70, v70
	v_fmac_f32_e32 v73, v72, v72
	v_add_f32_e32 v66, v67, v69
	v_add_f32_e32 v67, v71, v73
	v_add_f32_e32 v66, v66, v67
	s_waitcnt vmcnt(1)
	v_add_f32_e32 v54, v54, v58
	v_add_f32_e32 v55, v55, v59
	v_add_f32_e32 v52, v52, v56
	v_add_f32_e32 v53, v53, v57
	s_waitcnt vmcnt(0)
	v_add_f32_e32 v56, v50, v62
	v_add_f32_e32 v57, v51, v63
	v_add_f32_e32 v58, v48, v60
	v_add_f32_e32 v59, v49, v61
	v_mul_f32_e32 v48, v53, v53
	v_mul_f32_e32 v49, v55, v55
	v_mul_f32_e32 v50, v59, v59
	v_mul_f32_e32 v51, v57, v57
	v_fmac_f32_e32 v48, v52, v52
	v_fmac_f32_e32 v49, v54, v54
	v_fmac_f32_e32 v50, v58, v58
	v_fmac_f32_e32 v51, v56, v56
	v_add_f32_e32 v48, v48, v49
	v_add_f32_e32 v49, v50, v51
	v_add_f32_e32 v48, v48, v49
	v_add_f32_e32 v48, v66, v48
	ds_bpermute_b32 v49, v120, v48
	v_cvt_pk_bf16_f32 v50, v52, v53
	v_cvt_pk_bf16_f32 v51, v54, v55
	v_cvt_pk_bf16_f32 v52, v58, v59
	v_cvt_pk_bf16_f32 v53, v56, v57
	s_waitcnt lgkmcnt(0)
	v_add_f32_e32 v48, v48, v49
	ds_bpermute_b32 v49, v116, v48
	global_store_dwordx4 v[76:77], v[50:53], off offset:256
	s_and_saveexec_b64 s[46:47], s[6:7]
	s_cbranch_execz .LBB0_284
	v_lshlrev_b64 v[50:51], 7, v[64:65]
	v_lshl_add_u64 v[50:51], s[22:23], 0, v[50:51]
	v_lshl_add_u64 v[50:51], s[44:45], 2, v[50:51]
	s_lshl_b32 s8, s57, 2
	v_lshl_add_u64 v[50:51], v[50:51], 0, s[8:9]
	s_waitcnt lgkmcnt(0)
	v_add_f32_e32 v48, v48, v49
	global_store_dword v[50:51], v48, off
.LBB0_284:
	s_or_b64 exec, exec, s[46:47]
	s_waitcnt lgkmcnt(0)
	v_add_u32_e32 v48, 0x90, v146
	v_cmp_lt_i32_e32 vcc, s69, v48
	s_and_saveexec_b64 s[18:19], vcc
	s_xor_b64 s[46:47], exec, s[18:19]
	v_add_u32_e32 v136, 0xffff8090, v146
	v_lshlrev_b64 v[50:51], 13, v[136:137]
	v_lshl_add_u64 v[50:51], s[14:15], 0, v[50:51]
	v_mov_b32_e32 v49, v137
	s_andn2_saveexec_b64 s[46:47], s[46:47]
	v_ashrrev_i32_e32 v49, 31, v48
	v_lshlrev_b64 v[50:51], 13, v[48:49]
	v_lshl_add_u64 v[50:51], s[12:13], 0, v[50:51]
	s_or_b64 exec, exec, s[46:47]
	v_lshl_add_u64 v[58:59], v[148:149], 2, v[50:51]
	global_load_dwordx4 v[50:53], v[58:59], off
	global_load_dwordx4 v[54:57], v[58:59], off offset:16
	v_lshlrev_b64 v[60:61], 12, v[48:49]
	v_lshl_add_u64 v[60:61], s[16:17], 0, v[60:61]
	v_lshl_add_u64 v[60:61], v[148:149], 1, v[60:61]
	s_waitcnt vmcnt(1)
	v_add_f32_e32 v52, v46, v52
	v_add_f32_e32 v53, v47, v53
	v_add_f32_e32 v50, v44, v50
	v_add_f32_e32 v51, v45, v51
	s_waitcnt vmcnt(0)
	v_add_f32_e32 v56, v42, v56
	v_add_f32_e32 v57, v43, v57
	v_add_f32_e32 v54, v40, v54
	v_add_f32_e32 v55, v41, v55
	v_cvt_pk_bf16_f32 v40, v50, v51
	v_cvt_pk_bf16_f32 v41, v52, v53
	v_mul_f32_e32 v51, v51, v51
	v_cvt_pk_bf16_f32 v42, v54, v55
	v_cvt_pk_bf16_f32 v43, v56, v57
	global_store_dwordx4 v[60:61], v[40:43], off
	global_load_dwordx4 v[40:43], v[58:59], off offset:512
	s_nop 0
	global_load_dwordx4 v[44:47], v[58:59], off offset:528
	v_mul_f32_e32 v53, v53, v53
	v_mul_f32_e32 v55, v55, v55
	v_mul_f32_e32 v57, v57, v57
	v_fmac_f32_e32 v51, v50, v50
	v_fmac_f32_e32 v53, v52, v52
	v_fmac_f32_e32 v55, v54, v54
	v_fmac_f32_e32 v57, v56, v56
	v_add_f32_e32 v50, v51, v53
	v_add_f32_e32 v51, v55, v57
	v_add_f32_e32 v50, v50, v51
	s_waitcnt vmcnt(1)
	v_add_f32_e32 v38, v38, v42
	v_add_f32_e32 v39, v39, v43
	v_add_f32_e32 v36, v36, v40
	v_add_f32_e32 v37, v37, v41
	s_waitcnt vmcnt(0)
	v_add_f32_e32 v40, v34, v46
	v_add_f32_e32 v41, v35, v47
	v_add_f32_e32 v42, v32, v44
	v_add_f32_e32 v43, v33, v45
	v_mul_f32_e32 v32, v37, v37
	v_mul_f32_e32 v33, v39, v39
	v_mul_f32_e32 v34, v43, v43
	v_mul_f32_e32 v35, v41, v41
	v_fmac_f32_e32 v32, v36, v36
	v_fmac_f32_e32 v33, v38, v38
	v_fmac_f32_e32 v34, v42, v42
	v_fmac_f32_e32 v35, v40, v40
	v_add_f32_e32 v32, v32, v33
	v_add_f32_e32 v33, v34, v35
	v_add_f32_e32 v32, v32, v33
	v_add_f32_e32 v32, v50, v32
	ds_bpermute_b32 v33, v120, v32
	v_cvt_pk_bf16_f32 v34, v36, v37
	v_cvt_pk_bf16_f32 v35, v38, v39
	v_cvt_pk_bf16_f32 v36, v42, v43
	v_cvt_pk_bf16_f32 v37, v40, v41
	s_waitcnt lgkmcnt(0)
	v_add_f32_e32 v32, v32, v33
	ds_bpermute_b32 v33, v116, v32
	global_store_dwordx4 v[60:61], v[34:37], off offset:256
	s_and_saveexec_b64 s[46:47], s[6:7]
	s_cbranch_execz .LBB0_290
	v_lshlrev_b64 v[34:35], 7, v[48:49]
	v_lshl_add_u64 v[34:35], s[22:23], 0, v[34:35]
	v_lshl_add_u64 v[34:35], s[44:45], 2, v[34:35]
	s_lshl_b32 s8, s57, 2
	v_lshl_add_u64 v[34:35], v[34:35], 0, s[8:9]
	s_waitcnt lgkmcnt(0)
	v_add_f32_e32 v32, v32, v33
	global_store_dword v[34:35], v32, off
; __device__ __forceinline__ unsigned cvt_pk_bf16(float lo, float hi) { unsigned r; asm volatile("v_cvt_pk_bf16_f32 %0, %1, %2" : "=v"(r) : "v"(lo), "v"(hi)); return r; }
;     __device__ __forceinline__ void operator()(const f32x4 (&acc)[2][2][4][2], const Unit& u, int wr, int wc, int fr, int fq) const {
;     ...
;             for (int m = 0; m < 4; ++m) { const int row = u.pm * BM + ai * HALF + wr * 64 + m * 16 + fr;
;                 const float* xr = (row < 32768 ? xp + (size_t)row * 2048 : xs + (size_t)(row - 32768) * 2048) + col0; bf16_t* zrow = zb + (size_t)row * 2048 + col0;
;                 float s = 0.f;
; #pragma unroll
;                 for (int bj = 0; bj < 2; ++bj) { const f32x4 v0 = *(const f32x4*)(xr + bj * HALF) + acc[ai][bj][m][0], v1 = *(const f32x4*)(xr + bj * HALF + 4) + acc[ai][bj][m][1];
;                     s += ((v0[0] * v0[0] + v0[1] * v0[1]) + (v0[2] * v0[2] + v0[3] * v0[3])) + ((v1[0] * v1[0] + v1[1] * v1[1]) + (v1[2] * v1[2] + v1[3] * v1[3]));
;                     u32x4 w; w.x = cvt_pk_bf16(v0[0], v0[1]); w.y = cvt_pk_bf16(v0[2], v0[3]); w.z = cvt_pk_bf16(v1[0], v1[1]); w.w = cvt_pk_bf16(v1[2], v1[3]);
;                     *(u32x4*)(zrow + bj * HALF) = w; }
;                 s += __shfl_xor(s, 16); s += __shfl_xor(s, 32);
;                 if (fq == 0) part[(size_t)row * 32 + u.pn * 4 + wc] = s; }
.LBB0_290:
	s_or_b64 exec, exec, s[46:47]
	s_waitcnt lgkmcnt(0)
	v_add_u32_e32 v32, 0xa0, v146
	v_cmp_lt_i32_e32 vcc, s69, v32
	s_and_saveexec_b64 s[18:19], vcc
	s_xor_b64 s[46:47], exec, s[18:19]
	v_add_u32_e32 v136, 0xffff80a0, v146
	v_lshlrev_b64 v[34:35], 13, v[136:137]
	v_lshl_add_u64 v[34:35], s[14:15], 0, v[34:35]
	v_mov_b32_e32 v33, v137
	s_andn2_saveexec_b64 s[46:47], s[46:47]
	v_ashrrev_i32_e32 v33, 31, v32
	v_lshlrev_b64 v[34:35], 13, v[32:33]
	v_lshl_add_u64 v[34:35], s[12:13], 0, v[34:35]
	s_or_b64 exec, exec, s[46:47]
	v_lshl_add_u64 v[42:43], v[148:149], 2, v[34:35]
	global_load_dwordx4 v[34:37], v[42:43], off
	global_load_dwordx4 v[38:41], v[42:43], off offset:16
	v_lshlrev_b64 v[44:45], 12, v[32:33]
	v_lshl_add_u64 v[44:45], s[16:17], 0, v[44:45]
	v_lshl_add_u64 v[44:45], v[148:149], 1, v[44:45]
	s_waitcnt vmcnt(1)
	v_add_f32_e32 v36, v30, v36
	v_add_f32_e32 v37, v31, v37
	v_add_f32_e32 v34, v28, v34
	v_add_f32_e32 v35, v29, v35
	s_waitcnt vmcnt(0)
	v_add_f32_e32 v40, v26, v40
	v_add_f32_e32 v41, v27, v41
	v_add_f32_e32 v38, v24, v38
	v_add_f32_e32 v39, v25, v39
	v_cvt_pk_bf16_f32 v24, v34, v35
	v_cvt_pk_bf16_f32 v25, v36, v37
	v_mul_f32_e32 v35, v35, v35
	v_cvt_pk_bf16_f32 v26, v38, v39
	v_cvt_pk_bf16_f32 v27, v40, v41
	global_store_dwordx4 v[44:45], v[24:27], off
	global_load_dwordx4 v[24:27], v[42:43], off offset:512
	s_nop 0
	global_load_dwordx4 v[28:31], v[42:43], off offset:528
	v_mul_f32_e32 v37, v37, v37
	v_mul_f32_e32 v39, v39, v39
	v_mul_f32_e32 v41, v41, v41
	v_fmac_f32_e32 v35, v34, v34
	v_fmac_f32_e32 v37, v36, v36
	v_fmac_f32_e32 v39, v38, v38
	v_fmac_f32_e32 v41, v40, v40
	v_add_f32_e32 v34, v35, v37
	v_add_f32_e32 v35, v39, v41
	v_add_f32_e32 v34, v34, v35
	s_waitcnt vmcnt(1)
	v_add_f32_e32 v22, v22, v26
	v_add_f32_e32 v23, v23, v27
	v_add_f32_e32 v20, v20, v24
	v_add_f32_e32 v21, v21, v25
	s_waitcnt vmcnt(0)
	v_add_f32_e32 v24, v18, v30
	v_add_f32_e32 v25, v19, v31
	v_add_f32_e32 v26, v16, v28
	v_add_f32_e32 v27, v17, v29
	v_mul_f32_e32 v16, v21, v21
	v_mul_f32_e32 v17, v23, v23
	v_mul_f32_e32 v18, v27, v27
	v_mul_f32_e32 v19, v25, v25
	v_fmac_f32_e32 v16, v20, v20
	v_fmac_f32_e32 v17, v22, v22
	v_fmac_f32_e32 v18, v26, v26
	v_fmac_f32_e32 v19, v24, v24
	v_add_f32_e32 v16, v16, v17
	v_add_f32_e32 v17, v18, v19
	v_add_f32_e32 v16, v16, v17
	v_add_f32_e32 v16, v34, v16
	ds_bpermute_b32 v17, v120, v16
	v_cvt_pk_bf16_f32 v18, v20, v21
	v_cvt_pk_bf16_f32 v19, v22, v23
	v_cvt_pk_bf16_f32 v20, v26, v27
	v_cvt_pk_bf16_f32 v21, v24, v25
	s_waitcnt lgkmcnt(0)
	v_add_f32_e32 v16, v16, v17
	ds_bpermute_b32 v17, v116, v16
	global_store_dwordx4 v[44:45], v[18:21], off offset:256
	s_and_saveexec_b64 s[46:47], s[6:7]
	s_cbranch_execz .LBB0_296
	v_lshlrev_b64 v[18:19], 7, v[32:33]
	v_lshl_add_u64 v[18:19], s[22:23], 0, v[18:19]
	v_lshl_add_u64 v[18:19], s[44:45], 2, v[18:19]
	s_lshl_b32 s8, s57, 2
	v_lshl_add_u64 v[18:19], v[18:19], 0, s[8:9]
	s_waitcnt lgkmcnt(0)
	v_add_f32_e32 v16, v16, v17
	global_store_dword v[18:19], v16, off
.LBB0_296:
	s_or_b64 exec, exec, s[46:47]
	s_waitcnt lgkmcnt(0)
	v_add_u32_e32 v16, 0xb0, v146
	v_cmp_lt_i32_e32 vcc, s69, v16
	s_and_saveexec_b64 s[18:19], vcc
	s_xor_b64 s[46:47], exec, s[18:19]
	v_add_u32_e32 v136, 0xffff80b0, v146
	v_lshlrev_b64 v[18:19], 13, v[136:137]
	v_lshl_add_u64 v[18:19], s[14:15], 0, v[18:19]
	v_mov_b32_e32 v17, v137
	s_andn2_saveexec_b64 s[46:47], s[46:47]
	v_ashrrev_i32_e32 v17, 31, v16
	v_lshlrev_b64 v[18:19], 13, v[16:17]
	v_lshl_add_u64 v[18:19], s[12:13], 0, v[18:19]
	s_or_b64 exec, exec, s[46:47]
	v_lshl_add_u64 v[26:27], v[148:149], 2, v[18:19]
	global_load_dwordx4 v[18:21], v[26:27], off
	global_load_dwordx4 v[22:25], v[26:27], off offset:16
	v_lshlrev_b64 v[28:29], 12, v[16:17]
	v_lshl_add_u64 v[28:29], s[16:17], 0, v[28:29]
	v_lshl_add_u64 v[28:29], v[148:149], 1, v[28:29]
	s_waitcnt vmcnt(1)
	v_add_f32_e32 v20, v14, v20
	v_add_f32_e32 v21, v15, v21
	v_add_f32_e32 v18, v12, v18
	v_add_f32_e32 v19, v13, v19
	s_waitcnt vmcnt(0)
	v_add_f32_e32 v24, v10, v24
	v_add_f32_e32 v25, v11, v25
	v_add_f32_e32 v22, v8, v22
	v_add_f32_e32 v23, v9, v23
	v_cvt_pk_bf16_f32 v8, v18, v19
	v_cvt_pk_bf16_f32 v9, v20, v21
	v_mul_f32_e32 v19, v19, v19
	v_cvt_pk_bf16_f32 v10, v22, v23
	v_cvt_pk_bf16_f32 v11, v24, v25
	global_store_dwordx4 v[28:29], v[8:11], off
	global_load_dwordx4 v[8:11], v[26:27], off offset:512
	s_nop 0
	global_load_dwordx4 v[12:15], v[26:27], off offset:528
	v_mul_f32_e32 v21, v21, v21
	v_mul_f32_e32 v23, v23, v23
	v_mul_f32_e32 v25, v25, v25
	v_fmac_f32_e32 v19, v18, v18
	v_fmac_f32_e32 v21, v20, v20
	v_fmac_f32_e32 v23, v22, v22
	v_fmac_f32_e32 v25, v24, v24
	v_add_f32_e32 v18, v19, v21
	v_add_f32_e32 v19, v23, v25
	v_add_f32_e32 v18, v18, v19
	s_waitcnt vmcnt(1)
	v_add_f32_e32 v6, v6, v10
	v_add_f32_e32 v7, v7, v11
	v_add_f32_e32 v4, v4, v8
	v_add_f32_e32 v5, v5, v9
	s_waitcnt vmcnt(0)
	v_add_f32_e32 v8, v2, v14
	v_add_f32_e32 v9, v3, v15
	v_add_f32_e32 v10, v0, v12
	v_add_f32_e32 v11, v1, v13
	v_mul_f32_e32 v0, v5, v5
	v_mul_f32_e32 v1, v7, v7
	v_mul_f32_e32 v2, v11, v11
	v_mul_f32_e32 v3, v9, v9
	v_fmac_f32_e32 v0, v4, v4
	v_fmac_f32_e32 v1, v6, v6
	v_fmac_f32_e32 v2, v10, v10
	v_fmac_f32_e32 v3, v8, v8
	v_add_f32_e32 v0, v0, v1
	v_add_f32_e32 v1, v2, v3
	v_add_f32_e32 v0, v0, v1
	v_add_f32_e32 v0, v18, v0
	ds_bpermute_b32 v1, v120, v0
	v_cvt_pk_bf16_f32 v2, v4, v5
	v_cvt_pk_bf16_f32 v3, v6, v7
	v_cvt_pk_bf16_f32 v4, v10, v11
	v_cvt_pk_bf16_f32 v5, v8, v9
	s_waitcnt lgkmcnt(0)
	v_add_f32_e32 v0, v0, v1
	ds_bpermute_b32 v1, v116, v0
	global_store_dwordx4 v[28:29], v[2:5], off offset:256
	s_and_saveexec_b64 s[46:47], s[6:7]
	s_cbranch_execz .LBB0_302
	v_lshlrev_b64 v[2:3], 7, v[16:17]
	v_lshl_add_u64 v[2:3], s[22:23], 0, v[2:3]
	v_lshl_add_u64 v[2:3], s[44:45], 2, v[2:3]
	s_lshl_b32 s8, s57, 2
	v_lshl_add_u64 v[2:3], v[2:3], 0, s[8:9]
	s_waitcnt lgkmcnt(0)
	v_add_f32_e32 v0, v0, v1
	global_store_dword v[2:3], v0, off
